# P0 prologue stores (XN, bf16 weights, rope, W1S, TW zero fill) sc1, on top of v101
# speedup vs baseline: 1.0180x; 1.0014x over previous
.LBB0_21:
	s_waitcnt lgkmcnt(3)
	v_cvt_pk_bf16_f32 v64, v64, v65
	s_waitcnt lgkmcnt(2)
	v_cvt_pk_bf16_f32 v65, v66, v67
	s_waitcnt lgkmcnt(1)
	v_cvt_pk_bf16_f32 v66, v68, v69
	v_mad_i64_i32 v[68:69], s[38:39], v73, s60, 0
	v_lshl_add_u64 v[68:69], v[68:69], 1, s[6:7]
	v_lshl_add_u64 v[68:69], s[0:1], 1, v[68:69]
	v_mov_b32_e32 v99, v97
	s_waitcnt lgkmcnt(0)
	v_cvt_pk_bf16_f32 v67, v70, v71
	v_lshl_add_u64 v[68:69], v[68:69], 0, v[98:99]
	global_store_dwordx4 v[68:69], v[64:67], off sc1
	s_waitcnt lgkmcnt(0)

.LBB0_119:
	s_waitcnt lgkmcnt(0)
	v_cvt_pk_bf16_f32 v64, v64, v65
	v_cvt_pk_bf16_f32 v65, v66, v67
	v_cvt_pk_bf16_f32 v66, v68, v69
	v_ashrrev_i32_e32 v68, 31, v87
	v_cvt_pk_bf16_f32 v67, v70, v71
	v_mul_lo_u32 v70, s39, v87
	v_mul_lo_u32 v71, s38, v68
	v_mad_u64_u32 v[68:69], s[0:1], s38, v87, 0
	v_add3_u32 v69, v69, v71, v70
	s_ashr_i32 s43, s42, 31
	v_lshl_add_u64 v[68:69], v[68:69], 1, s[40:41]
	v_lshl_add_u64 v[68:69], s[42:43], 1, v[68:69]
	v_mov_b32_e32 v99, v97
	v_lshl_add_u64 v[68:69], v[68:69], 0, v[98:99]
	global_store_dwordx4 v[68:69], v[64:67], off sc1
	ds_read2_b32 v[64:65], v113 offset0:8 offset1:41
	ds_read2_b32 v[66:67], v113 offset0:74 offset1:107
	ds_read2_b32 v[68:69], v113 offset0:140 offset1:173
	ds_read2_b32 v[70:71], v113 offset0:206 offset1:239
	v_or_b32_e32 v86, s44, v107
	s_cmp_gt_i32 s63, 1
	s_mov_b64 s[0:1], -1
	s_cbranch_scc0 .LBB0_121
	v_and_b32_e32 v87, 0x6f, v86
	v_or_b32_e32 v87, s45, v87
	s_mov_b64 s[0:1], 0

.LBB0_125:
	s_waitcnt lgkmcnt(3)
	v_cvt_pk_bf16_f32 v64, v64, v65
	s_waitcnt lgkmcnt(2)
	v_cvt_pk_bf16_f32 v65, v66, v67
	s_waitcnt lgkmcnt(1)
	v_cvt_pk_bf16_f32 v66, v68, v69
	v_ashrrev_i32_e32 v68, 31, v87
	s_waitcnt lgkmcnt(0)
	v_cvt_pk_bf16_f32 v67, v70, v71
	v_mul_lo_u32 v70, s39, v87
	v_mul_lo_u32 v71, s38, v68
	v_mad_u64_u32 v[68:69], s[0:1], s38, v87, 0
	v_add3_u32 v69, v69, v71, v70
	v_lshl_add_u64 v[68:69], v[68:69], 1, s[40:41]
	v_lshl_add_u64 v[68:69], s[42:43], 1, v[68:69]
	v_mov_b32_e32 v99, v97
	v_lshl_add_u64 v[68:69], v[68:69], 0, v[98:99]
	global_store_dwordx4 v[68:69], v[64:67], off sc1
	ds_read2_b32 v[64:65], v113 offset0:16 offset1:49
	ds_read2_b32 v[66:67], v113 offset0:82 offset1:115
	ds_read2_b32 v[68:69], v113 offset0:148 offset1:181
	ds_read2_b32 v[70:71], v113 offset0:214 offset1:247
	v_or_b32_e32 v86, s44, v109
	s_cmp_gt_i32 s63, 1
	s_mov_b64 s[0:1], -1
	s_cbranch_scc0 .LBB0_127
	v_and_b32_e32 v87, 0x77, v86
	v_or_b32_e32 v87, s45, v87
	s_mov_b64 s[0:1], 0

.LBB0_131:
	s_waitcnt lgkmcnt(3)
	v_cvt_pk_bf16_f32 v64, v64, v65
	s_waitcnt lgkmcnt(2)
	v_cvt_pk_bf16_f32 v65, v66, v67
	s_waitcnt lgkmcnt(1)
	v_cvt_pk_bf16_f32 v66, v68, v69
	v_ashrrev_i32_e32 v68, 31, v87
	s_waitcnt lgkmcnt(0)
	v_cvt_pk_bf16_f32 v67, v70, v71
	v_mul_lo_u32 v70, s39, v87
	v_mul_lo_u32 v71, s38, v68
	v_mad_u64_u32 v[68:69], s[0:1], s38, v87, 0
	v_add3_u32 v69, v69, v71, v70
	v_lshl_add_u64 v[68:69], v[68:69], 1, s[40:41]
	v_lshl_add_u64 v[68:69], s[42:43], 1, v[68:69]
	v_mov_b32_e32 v99, v97
	v_lshl_add_u64 v[68:69], v[68:69], 0, v[98:99]
	global_store_dwordx4 v[68:69], v[64:67], off sc1
	ds_read2_b32 v[64:65], v113 offset0:24 offset1:57
	ds_read2_b32 v[66:67], v113 offset0:90 offset1:123
	ds_read2_b32 v[68:69], v113 offset0:156 offset1:189
	ds_read2_b32 v[70:71], v113 offset0:222 offset1:255
	v_or_b32_e32 v86, s44, v111
	s_cmp_gt_i32 s63, 1
	s_mov_b64 s[0:1], -1
	s_cbranch_scc0 .LBB0_133
	v_and_b32_e32 v87, 0x7f, v86
	v_or_b32_e32 v87, s45, v87
	s_mov_b64 s[0:1], 0

.LBB0_137:
	s_waitcnt lgkmcnt(3)
	v_cvt_pk_bf16_f32 v64, v64, v65
	s_waitcnt lgkmcnt(2)
	v_cvt_pk_bf16_f32 v65, v66, v67
	s_waitcnt lgkmcnt(1)
	v_cvt_pk_bf16_f32 v66, v68, v69
	v_ashrrev_i32_e32 v68, 31, v87
	s_waitcnt lgkmcnt(0)
	v_cvt_pk_bf16_f32 v67, v70, v71
	v_mul_lo_u32 v70, s39, v87
	v_mul_lo_u32 v71, s38, v68
	v_mad_u64_u32 v[68:69], s[0:1], s38, v87, 0
	v_add3_u32 v69, v69, v71, v70
	v_lshl_add_u64 v[68:69], v[68:69], 1, s[40:41]
	v_lshl_add_u64 v[68:69], s[42:43], 1, v[68:69]
	v_mov_b32_e32 v99, v97
	v_lshl_add_u64 v[68:69], v[68:69], 0, v[98:99]
	global_store_dwordx4 v[68:69], v[64:67], off sc1
	s_waitcnt lgkmcnt(0)
	s_andn2_b64 vcc, exec, s[46:47]
	s_cbranch_vccz .LBB0_139
	s_andn2_b64 vcc, exec, s[48:49]
	s_cbranch_vccnz .LBB0_22
	s_branch .LBB0_172

.LBB0_147:
	s_lshl_b32 s0, s38, 6
	s_waitcnt lgkmcnt(3)
	v_cvt_pk_bf16_f32 v64, v64, v65
	s_waitcnt lgkmcnt(2)
	v_cvt_pk_bf16_f32 v65, v66, v67
	s_waitcnt lgkmcnt(1)
	v_cvt_pk_bf16_f32 v66, v68, v69
	v_mad_i64_i32 v[68:69], s[38:39], v87, s58, 0
	s_ashr_i32 s1, s0, 31
	v_lshl_add_u64 v[68:69], v[68:69], 1, s[4:5]
	v_lshl_add_u64 v[68:69], s[0:1], 1, v[68:69]
	v_mov_b32_e32 v99, v97
	s_waitcnt lgkmcnt(0)
	v_cvt_pk_bf16_f32 v67, v70, v71
	v_lshl_add_u64 v[68:69], v[68:69], 0, v[98:99]
	global_store_dwordx4 v[68:69], v[64:67], off sc1
	ds_read2_b32 v[64:65], v113 offset0:8 offset1:41
	ds_read2_b32 v[66:67], v113 offset0:74 offset1:107
	ds_read2_b32 v[68:69], v113 offset0:140 offset1:173
	ds_read2_b32 v[70:71], v113 offset0:206 offset1:239
	v_or_b32_e32 v86, s41, v107
	s_cmp_lt_i32 s61, 2
	s_mov_b64 s[38:39], -1
	s_cbranch_scc1 .LBB0_151
	s_cmp_eq_u32 s61, 2
	v_mov_b32_e32 v87, v86
	s_cbranch_scc0 .LBB0_150
	v_and_b32_e32 v87, 0x6f, v86
	v_or_b32_e32 v87, s40, v87

.LBB0_155:
	s_waitcnt lgkmcnt(3)
	v_cvt_pk_bf16_f32 v64, v64, v65
	s_waitcnt lgkmcnt(2)
	v_cvt_pk_bf16_f32 v65, v66, v67
	s_waitcnt lgkmcnt(1)
	v_cvt_pk_bf16_f32 v66, v68, v69
	v_mad_i64_i32 v[68:69], s[38:39], v87, s58, 0
	v_lshl_add_u64 v[68:69], v[68:69], 1, s[4:5]
	v_lshl_add_u64 v[68:69], s[0:1], 1, v[68:69]
	v_mov_b32_e32 v99, v97
	s_waitcnt lgkmcnt(0)
	v_cvt_pk_bf16_f32 v67, v70, v71
	v_lshl_add_u64 v[68:69], v[68:69], 0, v[98:99]
	global_store_dwordx4 v[68:69], v[64:67], off sc1
	ds_read2_b32 v[64:65], v113 offset0:16 offset1:49
	ds_read2_b32 v[66:67], v113 offset0:82 offset1:115
	ds_read2_b32 v[68:69], v113 offset0:148 offset1:181
	ds_read2_b32 v[70:71], v113 offset0:214 offset1:247
	v_or_b32_e32 v86, s41, v109
	s_cmp_lt_i32 s61, 2
	s_mov_b64 s[38:39], -1
	s_cbranch_scc1 .LBB0_159
	s_cmp_eq_u32 s61, 2
	v_mov_b32_e32 v87, v86
	s_cbranch_scc0 .LBB0_158
	v_and_b32_e32 v87, 0x77, v86
	v_or_b32_e32 v87, s40, v87

.LBB0_163:
	s_waitcnt lgkmcnt(3)
	v_cvt_pk_bf16_f32 v64, v64, v65
	s_waitcnt lgkmcnt(2)
	v_cvt_pk_bf16_f32 v65, v66, v67
	s_waitcnt lgkmcnt(1)
	v_cvt_pk_bf16_f32 v66, v68, v69
	v_mad_i64_i32 v[68:69], s[38:39], v87, s58, 0
	v_lshl_add_u64 v[68:69], v[68:69], 1, s[4:5]
	v_lshl_add_u64 v[68:69], s[0:1], 1, v[68:69]
	v_mov_b32_e32 v99, v97
	s_waitcnt lgkmcnt(0)
	v_cvt_pk_bf16_f32 v67, v70, v71
	v_lshl_add_u64 v[68:69], v[68:69], 0, v[98:99]
	global_store_dwordx4 v[68:69], v[64:67], off sc1
	ds_read2_b32 v[64:65], v113 offset0:24 offset1:57
	ds_read2_b32 v[66:67], v113 offset0:90 offset1:123
	ds_read2_b32 v[68:69], v113 offset0:156 offset1:189
	ds_read2_b32 v[70:71], v113 offset0:222 offset1:255
	v_or_b32_e32 v86, s41, v111
	s_cmp_lt_i32 s61, 2
	s_mov_b64 s[38:39], -1
	s_cbranch_scc1 .LBB0_167
	s_cmp_eq_u32 s61, 2
	v_mov_b32_e32 v87, v86
	s_cbranch_scc0 .LBB0_166
	v_and_b32_e32 v87, 0x7f, v86
	v_or_b32_e32 v87, s40, v87

.LBB0_171:
	s_waitcnt lgkmcnt(3)
	v_cvt_pk_bf16_f32 v64, v64, v65
	s_waitcnt lgkmcnt(2)
	v_cvt_pk_bf16_f32 v65, v66, v67
	s_waitcnt lgkmcnt(1)
	v_cvt_pk_bf16_f32 v66, v68, v69
	v_mad_i64_i32 v[68:69], s[38:39], v87, s58, 0
	v_lshl_add_u64 v[68:69], v[68:69], 1, s[4:5]
	v_lshl_add_u64 v[68:69], s[0:1], 1, v[68:69]
	v_mov_b32_e32 v99, v97
	s_waitcnt lgkmcnt(0)
	v_cvt_pk_bf16_f32 v67, v70, v71
	v_lshl_add_u64 v[68:69], v[68:69], 0, v[98:99]
	global_store_dwordx4 v[68:69], v[64:67], off sc1
	s_waitcnt lgkmcnt(0)
	s_andn2_b64 vcc, exec, s[48:49]
	s_cbranch_vccnz .LBB0_22

.LBB0_180:
	s_lshl_b32 s0, s38, 6
	s_waitcnt lgkmcnt(3)
	v_cvt_pk_bf16_f32 v64, v64, v65
	s_waitcnt lgkmcnt(2)
	v_cvt_pk_bf16_f32 v65, v66, v67
	s_waitcnt lgkmcnt(1)
	v_cvt_pk_bf16_f32 v66, v68, v69
	v_mad_i64_i32 v[68:69], s[38:39], v73, s60, 0
	s_ashr_i32 s1, s0, 31
	v_lshl_add_u64 v[68:69], v[68:69], 1, s[6:7]
	v_lshl_add_u64 v[68:69], s[0:1], 1, v[68:69]
	v_mov_b32_e32 v99, v97
	s_waitcnt lgkmcnt(0)
	v_cvt_pk_bf16_f32 v67, v70, v71
	v_lshl_add_u64 v[68:69], v[68:69], 0, v[98:99]
	global_store_dwordx4 v[68:69], v[64:67], off sc1
	ds_read2_b32 v[64:65], v113 offset0:8 offset1:41
	ds_read2_b32 v[66:67], v113 offset0:74 offset1:107
	ds_read2_b32 v[68:69], v113 offset0:140 offset1:173
	ds_read2_b32 v[70:71], v113 offset0:206 offset1:239
	v_or_b32_e32 v72, s41, v107
	s_cmp_lt_i32 s62, 2
	s_mov_b64 s[38:39], -1
	s_cbranch_scc1 .LBB0_184
	s_cmp_eq_u32 s62, 2
	v_mov_b32_e32 v73, v72
	s_cbranch_scc0 .LBB0_183
	v_and_b32_e32 v73, 0x6f, v72
	v_or_b32_e32 v73, s40, v73

.LBB0_188:
	s_waitcnt lgkmcnt(3)
	v_cvt_pk_bf16_f32 v64, v64, v65
	s_waitcnt lgkmcnt(2)
	v_cvt_pk_bf16_f32 v65, v66, v67
	s_waitcnt lgkmcnt(1)
	v_cvt_pk_bf16_f32 v66, v68, v69
	v_mad_i64_i32 v[68:69], s[38:39], v73, s60, 0
	v_lshl_add_u64 v[68:69], v[68:69], 1, s[6:7]
	v_lshl_add_u64 v[68:69], s[0:1], 1, v[68:69]
	v_mov_b32_e32 v99, v97
	s_waitcnt lgkmcnt(0)
	v_cvt_pk_bf16_f32 v67, v70, v71
	v_lshl_add_u64 v[68:69], v[68:69], 0, v[98:99]
	global_store_dwordx4 v[68:69], v[64:67], off sc1
	ds_read2_b32 v[64:65], v113 offset0:16 offset1:49
	ds_read2_b32 v[66:67], v113 offset0:82 offset1:115
	ds_read2_b32 v[68:69], v113 offset0:148 offset1:181
	ds_read2_b32 v[70:71], v113 offset0:214 offset1:247
	v_or_b32_e32 v72, s41, v109
	s_cmp_lt_i32 s62, 2
	s_mov_b64 s[38:39], -1
	s_cbranch_scc1 .LBB0_192
	s_cmp_eq_u32 s62, 2
	v_mov_b32_e32 v73, v72
	s_cbranch_scc0 .LBB0_191
	v_and_b32_e32 v73, 0x77, v72
	v_or_b32_e32 v73, s40, v73

.LBB0_196:
	s_waitcnt lgkmcnt(3)
	v_cvt_pk_bf16_f32 v64, v64, v65
	s_waitcnt lgkmcnt(2)
	v_cvt_pk_bf16_f32 v65, v66, v67
	s_waitcnt lgkmcnt(1)
	v_cvt_pk_bf16_f32 v66, v68, v69
	v_mad_i64_i32 v[68:69], s[38:39], v73, s60, 0
	v_lshl_add_u64 v[68:69], v[68:69], 1, s[6:7]
	v_lshl_add_u64 v[68:69], s[0:1], 1, v[68:69]
	v_mov_b32_e32 v99, v97
	s_waitcnt lgkmcnt(0)
	v_cvt_pk_bf16_f32 v67, v70, v71
	v_lshl_add_u64 v[68:69], v[68:69], 0, v[98:99]
	global_store_dwordx4 v[68:69], v[64:67], off sc1
	ds_read2_b32 v[64:65], v113 offset0:24 offset1:57
	ds_read2_b32 v[66:67], v113 offset0:90 offset1:123
	ds_read2_b32 v[68:69], v113 offset0:156 offset1:189
	ds_read2_b32 v[70:71], v113 offset0:222 offset1:255
	v_or_b32_e32 v72, s41, v111
	s_cmp_lt_i32 s62, 2
	s_mov_b64 s[38:39], -1
	s_cbranch_scc1 .LBB0_200
	s_cmp_eq_u32 s62, 2
	v_mov_b32_e32 v73, v72
	s_cbranch_scc0 .LBB0_199
	v_and_b32_e32 v73, 0x7f, v72
	v_or_b32_e32 v73, s40, v73

.LBB0_213:
	s_or_b64 exec, exec, s[6:7]
	v_div_scale_f32 v47, s[6:7], v46, v46, 1.0
	v_rcp_f32_e32 v48, v47
	s_lshl_b64 s[6:7], s[36:37], 10
	v_fma_f32 v49, -v47, v48, 1.0
	v_fmac_f32_e32 v48, v49, v48
	v_div_scale_f32 v49, vcc, 1.0, v46, 1.0
	v_mul_f32_e32 v50, v49, v48
	v_fma_f32 v51, -v47, v50, v49
	v_fmac_f32_e32 v50, v51, v48
	v_fma_f32 v47, -v47, v50, v49
	v_div_fmas_f32 v47, v47, v48, v50
	v_div_fixup_f32 v46, v47, v46, 1.0
	v_pk_mul_f32 v[12:13], v[46:47], v[12:13] op_sel_hi:[0,1]
	v_pk_mul_f32 v[14:15], v[46:47], v[14:15] op_sel_hi:[0,1]
	v_pk_mul_f32 v[8:9], v[46:47], v[8:9] op_sel_hi:[0,1]
	v_pk_mul_f32 v[10:11], v[46:47], v[10:11] op_sel_hi:[0,1]
	v_pk_mul_f32 v[4:5], v[46:47], v[4:5] op_sel_hi:[0,1]
	v_pk_mul_f32 v[6:7], v[46:47], v[6:7] op_sel_hi:[0,1]
	v_pk_mul_f32 v[0:1], v[46:47], v[0:1] op_sel_hi:[0,1]
	v_pk_mul_f32 v[2:3], v[46:47], v[2:3] op_sel_hi:[0,1]
	v_lshl_add_u64 v[48:49], s[6:7], 1, v[36:37]
	v_cvt_pk_bf16_f32 v12, v12, v13
	v_cvt_pk_bf16_f32 v13, v14, v15
	v_cvt_pk_bf16_f32 v8, v8, v9
	v_cvt_pk_bf16_f32 v9, v10, v11
	v_cvt_pk_bf16_f32 v4, v4, v5
	v_cvt_pk_bf16_f32 v5, v6, v7
	v_cvt_pk_bf16_f32 v0, v0, v1
	v_cvt_pk_bf16_f32 v1, v2, v3
	s_and_b64 vcc, exec, s[0:1]
	global_store_dwordx2 v[48:49], v[12:13], off sc1
	global_store_dwordx2 v[48:49], v[8:9], off offset:512 sc1
	global_store_dwordx2 v[48:49], v[4:5], off offset:1024 sc1
	global_store_dwordx2 v[48:49], v[0:1], off offset:1536 sc1
	s_cbranch_vccnz .LBB0_209
	v_div_scale_f32 v0, s[0:1], v45, v45, 1.0
	v_rcp_f32_e32 v1, v0
	v_div_scale_f32 v2, vcc, 1.0, v45, 1.0
	s_ashr_i32 s21, s20, 31
	v_fma_f32 v3, -v0, v1, 1.0
	v_fmac_f32_e32 v1, v3, v1
	v_mul_f32_e32 v3, v2, v1
	v_fma_f32 v4, -v0, v3, v2
	v_fmac_f32_e32 v3, v4, v1
	v_fma_f32 v0, -v0, v3, v2
	v_div_fmas_f32 v0, v0, v1, v3
	v_div_fixup_f32 v0, v0, v45, 1.0
	s_lshl_b64 s[0:1], s[20:21], 11
	v_pk_mul_f32 v[4:5], v[0:1], v[28:29] op_sel_hi:[0,1]
	v_pk_mul_f32 v[6:7], v[0:1], v[30:31] op_sel_hi:[0,1]
	v_lshl_add_u64 v[2:3], v[36:37], 0, s[0:1]
	v_cvt_pk_bf16_f32 v4, v4, v5
	v_cvt_pk_bf16_f32 v5, v6, v7
	global_store_dwordx2 v[2:3], v[4:5], off sc1
	v_pk_mul_f32 v[4:5], v[0:1], v[24:25] op_sel_hi:[0,1]
	v_pk_mul_f32 v[6:7], v[0:1], v[26:27] op_sel_hi:[0,1]
	v_cvt_pk_bf16_f32 v4, v4, v5
	v_cvt_pk_bf16_f32 v5, v6, v7
	global_store_dwordx2 v[2:3], v[4:5], off offset:512 sc1
	v_pk_mul_f32 v[4:5], v[0:1], v[20:21] op_sel_hi:[0,1]
	v_pk_mul_f32 v[6:7], v[0:1], v[22:23] op_sel_hi:[0,1]
	v_cvt_pk_bf16_f32 v4, v4, v5
	v_cvt_pk_bf16_f32 v5, v6, v7
	global_store_dwordx2 v[2:3], v[4:5], off offset:1024 sc1
	v_pk_mul_f32 v[4:5], v[0:1], v[16:17] op_sel_hi:[0,1]
	v_pk_mul_f32 v[0:1], v[0:1], v[18:19] op_sel_hi:[0,1]
	v_cvt_pk_bf16_f32 v4, v4, v5
	v_cvt_pk_bf16_f32 v5, v0, v1
	global_store_dwordx2 v[2:3], v[4:5], off offset:1536 sc1
	s_branch .LBB0_209

.LBB0_217:
	s_or_b64 exec, exec, s[0:1]
	v_mul_f32_e32 v15, v0, v0
	v_fmamk_f32 v16, v15, 0xb94c1982, v5
	v_fmaak_f32 v16, v15, v16, 0xbe2aaa9d
	v_mul_f32_e32 v16, v15, v16
	v_fmac_f32_e32 v0, v0, v16
	v_fmamk_f32 v16, v15, 0x37d75334, v7
	v_fmaak_f32 v16, v15, v16, 0x3d2aabf7
	v_fmaak_f32 v16, v15, v16, 0xbf000004
	v_fma_f32 v15, v15, v16, 1.0
	v_lshlrev_b32_e32 v16, 30, v14
	v_and_b32_e32 v14, 1, v14
	v_cmp_eq_u32_e32 vcc, 0, v14
	v_xor_b32_e32 v13, v13, v12
	v_and_b32_e32 v17, 0x80000000, v16
	v_cndmask_b32_e32 v14, v15, v0, vcc
	v_xor_b32_e32 v0, 0x80000000, v0
	v_xor_b32_e32 v13, v13, v14
	v_cndmask_b32_e32 v0, v0, v15, vcc
	v_xor_b32_e32 v13, v13, v17
	v_bitop3_b32 v0, v0, v16, s46 bitop3:0x78
	v_cmp_class_f32_e64 vcc, v12, s47
	v_add_u32_e32 v11, s18, v11
	s_nop 0
	v_cndmask_b32_e32 v12, v10, v0, vcc
	v_cndmask_b32_e32 v13, v10, v13, vcc
	v_cmp_lt_i32_e32 vcc, s48, v11
	global_store_dwordx2 v[2:3], v[12:13], off sc1
	s_or_b64 s[22:23], vcc, s[22:23]
	v_lshl_add_u64 v[2:3], v[2:3], 0, s[34:35]
	s_andn2_b64 exec, exec, s[22:23]
	s_cbranch_execz .LBB0_222

.LBB0_224:
	s_or_b64 exec, exec, s[0:1]
	s_waitcnt vmcnt(14)
	v_max_f32_e32 v10, v10, v10
	v_min_f32_e32 v10, 0xb8d1b717, v10
	v_mul_f32_e32 v9, v9, v10
	v_mul_f32_e32 v28, v9, v5
	v_mul_f32_e32 v29, 0x3fb8aa3b, v28
	v_fma_f32 v30, v28, s3, -v29
	v_rndne_f32_e32 v31, v29
	v_fmac_f32_e32 v30, 0x32a5705f, v28
	v_sub_f32_e32 v29, v29, v31
	v_add_f32_e32 v29, v29, v30
	v_cvt_i32_f32_e32 v30, v31
	v_exp_f32_e32 v29, v29
	v_cmp_ngt_f32_e32 vcc, s19, v28
	v_xor_b32_e32 v23, v23, v22
	v_cmp_ngt_f32_e64 s[0:1], s19, v9
	v_ldexp_f32 v29, v29, v30
	v_cndmask_b32_e32 v29, 0, v29, vcc
	v_cmp_nlt_f32_e32 vcc, s33, v28
	v_mul_f32_e32 v28, v25, v25
	v_xor_b32_e32 v24, v24, v13
	v_cndmask_b32_e32 v60, v14, v29, vcc
	v_fmamk_f32 v29, v28, 0xb94c1982, v15
	v_fmaak_f32 v29, v28, v29, 0xbe2aaa9d
	v_mul_f32_e32 v29, v28, v29
	v_fmac_f32_e32 v25, v25, v29
	v_fmamk_f32 v29, v28, 0x37d75334, v16
	v_fmaak_f32 v29, v28, v29, 0x3d2aabf7
	v_fmaak_f32 v29, v28, v29, 0xbf000004
	v_fma_f32 v28, v28, v29, 1.0
	v_lshlrev_b32_e32 v29, 30, v26
	v_and_b32_e32 v26, 1, v26
	v_cmp_eq_u32_e32 vcc, 0, v26
	v_and_b32_e32 v44, 0x80000000, v29
	v_lshl_or_b32 v8, v8, 7, v21
	v_cndmask_b32_e32 v26, v28, v25, vcc
	v_xor_b32_e32 v23, v23, v26
	v_xor_b32_e32 v25, 0x80000000, v25
	v_mul_f32_e32 v26, 0x3fb8aa3b, v9
	v_cndmask_b32_e32 v25, v25, v28, vcc
	v_fma_f32 v28, v9, s3, -v26
	v_rndne_f32_e32 v45, v26
	v_fmac_f32_e32 v28, 0x32a5705f, v9
	v_sub_f32_e32 v26, v26, v45
	v_add_f32_e32 v26, v26, v28
	v_lshlrev_b32_e32 v28, 4, v12
	v_ashrrev_i32_e32 v29, 31, v28
	v_lshlrev_b64 v[28:29], 2, v[28:29]
	v_lshl_add_u64 v[48:49], s[10:11], 0, v[28:29]
	v_lshl_add_u64 v[56:57], s[8:9], 0, v[28:29]
	global_load_dwordx4 v[28:31], v[48:49], off offset:16
	global_load_dwordx4 v[32:35], v[48:49], off
	global_load_dwordx4 v[36:39], v[56:57], off offset:16
	global_load_dwordx4 v[40:43], v[56:57], off
	v_xor_b32_e32 v23, v23, v44
	v_cvt_i32_f32_e32 v12, v45
	v_xor_b32_e32 v61, v25, v44
	global_load_dwordx4 v[44:47], v[48:49], off offset:48
	s_nop 0
	global_load_dwordx4 v[48:51], v[48:49], off offset:32
	s_nop 0
	global_load_dwordx4 v[52:55], v[56:57], off offset:48
	s_nop 0
	global_load_dwordx4 v[56:59], v[56:57], off offset:32
	v_exp_f32_e32 v26, v26
	v_cmp_class_f32_e64 vcc, v22, s48
	v_add_u32_e32 v20, s18, v20
	v_ldexp_f32 v12, v26, v12
	v_cndmask_b32_e64 v12, 0, v12, s[0:1]
	v_cmp_nlt_f32_e64 s[0:1], s33, v9
	v_and_b32_e32 v26, 1, v27
	v_cndmask_b32_e32 v23, v19, v23, vcc
	v_cndmask_b32_e64 v9, v14, v12, s[0:1]
	v_mul_f32_e32 v12, v0, v0
	v_fmamk_f32 v22, v12, 0xb94c1982, v15
	v_fmaak_f32 v22, v12, v22, 0xbe2aaa9d
	v_mul_f32_e32 v22, v12, v22
	v_fmac_f32_e32 v0, v0, v22
	v_fmamk_f32 v22, v12, 0x37d75334, v16
	v_fmaak_f32 v22, v12, v22, 0x3d2aabf7
	v_fmaak_f32 v22, v12, v22, 0xbf000004
	v_fma_f32 v12, v12, v22, 1.0
	v_cmp_eq_u32_e64 s[0:1], 0, v26
	v_lshlrev_b32_e32 v22, 30, v27
	v_and_b32_e32 v25, 0x80000000, v22
	v_cndmask_b32_e64 v26, v12, v0, s[0:1]
	v_xor_b32_e32 v0, 0x80000000, v0
	v_xor_b32_e32 v24, v24, v26
	v_cndmask_b32_e64 v0, v0, v12, s[0:1]
	v_xor_b32_e32 v24, v24, v25
	v_bitop3_b32 v0, v0, v22, s47 bitop3:0x78
	v_cmp_class_f32_e64 s[0:1], v13, s48
	v_cndmask_b32_e32 v22, v19, v61, vcc
	v_pk_mul_f32 v[22:23], v[60:61], v[22:23] op_sel_hi:[0,1]
	v_cndmask_b32_e64 v0, v19, v0, s[0:1]
	v_cndmask_b32_e64 v12, v19, v24, s[0:1]
	v_mul_f32_e32 v13, v9, v12
	v_fma_f32 v12, v9, v0, -1.0
	v_mov_b32_e32 v0, v11
	v_pk_mul_f32 v[24:25], v[10:11], v[10:11]
	v_pk_mul_f32 v[26:27], v[0:1], v[12:13] op_sel:[0,1] op_sel_hi:[0,0]
	v_pk_fma_f32 v[62:63], v[10:11], v[12:13], v[26:27] op_sel_hi:[0,1,1] neg_lo:[0,0,1] neg_hi:[0,0,1]
	v_pk_add_f32 v[24:25], v[24:25], v[24:25] op_sel:[0,1] op_sel_hi:[0,1]
	v_div_scale_f32 v0, s[0:1], v25, v25, v63
	v_rcp_f32_e32 v9, v0
	v_pk_fma_f32 v[10:11], v[10:11], v[12:13], v[26:27]
	s_nop 0
	v_fma_f32 v11, -v0, v9, 1.0
	v_fmac_f32_e32 v9, v11, v9
	v_div_scale_f32 v11, vcc, v63, v25, v63
	v_mul_f32_e32 v12, v11, v9
	v_fma_f32 v13, -v0, v12, v11
	v_fmac_f32_e32 v12, v13, v9
	v_div_scale_f32 v13, s[0:1], v24, v24, v10
	v_rcp_f32_e32 v26, v13
	v_fma_f32 v0, -v0, v12, v11
	v_div_fmas_f32 v0, v0, v9, v12
	v_div_fixup_f32 v11, v0, v25, v63
	v_fma_f32 v0, -v13, v26, 1.0
	v_fmac_f32_e32 v26, v0, v26
	v_div_scale_f32 v0, vcc, v10, v24, v10
	v_mul_f32_e32 v9, v0, v26
	v_fma_f32 v12, -v13, v9, v0
	v_fmac_f32_e32 v9, v12, v26
	v_fma_f32 v0, -v13, v9, v0
	v_div_fmas_f32 v0, v0, v26, v9
	v_div_fixup_f32 v10, v0, v24, v10
	v_pk_mul_f32 v[12:13], v[22:23], v[10:11]
	v_pk_mul_f32 v[10:11], v[22:23], v[10:11] op_sel:[0,1] op_sel_hi:[1,0]
	v_pk_add_f32 v[12:13], v[12:13], v[12:13] op_sel:[0,1] op_sel_hi:[0,1] neg_lo:[0,1] neg_hi:[0,1]
	v_pk_add_f32 v[10:11], v[10:11], v[10:11] op_sel:[0,1] op_sel_hi:[0,1]
	s_waitcnt vmcnt(6)
	v_pk_mul_f32 v[22:23], v[10:11], v[32:33]
	v_pk_mul_f32 v[24:25], v[12:13], v[32:33]
	v_pk_mul_f32 v[26:27], v[10:11], v[34:35]
	v_pk_mul_f32 v[32:33], v[12:13], v[34:35]
	v_pk_mul_f32 v[34:35], v[10:11], v[28:29]
	v_pk_mul_f32 v[28:29], v[12:13], v[28:29]
	s_waitcnt vmcnt(5)
	v_pk_fma_f32 v[34:35], v[12:13], v[36:37], v[34:35] neg_lo:[0,0,1] neg_hi:[0,0,1]
	v_pk_fma_f32 v[28:29], v[10:11], v[36:37], v[28:29]
	v_pk_mul_f32 v[36:37], v[10:11], v[30:31]
	v_pk_mul_f32 v[30:31], v[12:13], v[30:31]
	s_waitcnt vmcnt(4)
	v_pk_fma_f32 v[22:23], v[12:13], v[40:41], v[22:23] neg_lo:[0,0,1] neg_hi:[0,0,1]
	v_pk_fma_f32 v[24:25], v[10:11], v[40:41], v[24:25]
	v_pk_fma_f32 v[26:27], v[12:13], v[42:43], v[26:27] neg_lo:[0,0,1] neg_hi:[0,0,1]
	v_pk_fma_f32 v[32:33], v[10:11], v[42:43], v[32:33]
	v_pk_fma_f32 v[36:37], v[12:13], v[38:39], v[36:37] neg_lo:[0,0,1] neg_hi:[0,0,1]
	v_pk_fma_f32 v[30:31], v[10:11], v[38:39], v[30:31]
	s_waitcnt vmcnt(2)
	v_pk_mul_f32 v[38:39], v[10:11], v[48:49]
	v_pk_mul_f32 v[40:41], v[12:13], v[48:49]
	v_pk_mul_f32 v[42:43], v[10:11], v[50:51]
	v_pk_mul_f32 v[48:49], v[12:13], v[50:51]
	v_pk_mul_f32 v[50:51], v[10:11], v[44:45]
	v_pk_mul_f32 v[44:45], v[12:13], v[44:45]
	s_waitcnt vmcnt(1)
	v_pk_fma_f32 v[50:51], v[12:13], v[52:53], v[50:51] neg_lo:[0,0,1] neg_hi:[0,0,1]
	v_pk_fma_f32 v[44:45], v[10:11], v[52:53], v[44:45]
	v_pk_mul_f32 v[52:53], v[10:11], v[46:47]
	s_waitcnt vmcnt(0)
	v_pk_fma_f32 v[38:39], v[12:13], v[56:57], v[38:39] neg_lo:[0,0,1] neg_hi:[0,0,1]
	v_pk_fma_f32 v[42:43], v[12:13], v[58:59], v[42:43] neg_lo:[0,0,1] neg_hi:[0,0,1]
	v_pk_fma_f32 v[52:53], v[12:13], v[54:55], v[52:53] neg_lo:[0,0,1] neg_hi:[0,0,1]
	v_pk_mul_f32 v[12:13], v[12:13], v[46:47]
	v_ashrrev_i32_e32 v9, 31, v8
	v_pk_fma_f32 v[40:41], v[10:11], v[56:57], v[40:41]
	v_pk_fma_f32 v[48:49], v[10:11], v[58:59], v[48:49]
	v_pk_fma_f32 v[12:13], v[10:11], v[54:55], v[12:13]
	v_lshlrev_b64 v[10:11], 10, v[8:9]
	v_or_b32_e32 v8, 64, v8
	v_ashrrev_i32_e32 v9, 31, v8
	v_lshlrev_b64 v[8:9], 10, v[8:9]
	v_lshl_add_u64 v[46:47], v[2:3], 0, v[10:11]
	v_lshl_add_u64 v[54:55], v[2:3], 0, v[8:9]
	v_cvt_pk_bf16_f32 v8, v22, v23
	v_cvt_pk_bf16_f32 v9, v26, v27
	v_cvt_pk_bf16_f32 v10, v34, v35
	v_cvt_pk_bf16_f32 v11, v36, v37
	global_store_dwordx4 v[46:47], v[8:11], off sc1
	v_cmp_lt_i32_e32 vcc, s50, v20
	s_or_b64 s[22:23], vcc, s[22:23]
	v_cvt_pk_bf16_f32 v8, v38, v39
	v_cvt_pk_bf16_f32 v9, v42, v43
	v_cvt_pk_bf16_f32 v10, v50, v51
	v_cvt_pk_bf16_f32 v11, v52, v53
	global_store_dwordx4 v[46:47], v[8:11], off offset:16 sc1
	s_nop 1
	v_cvt_pk_bf16_f32 v8, v24, v25
	v_cvt_pk_bf16_f32 v9, v32, v33
	v_cvt_pk_bf16_f32 v10, v28, v29
	v_cvt_pk_bf16_f32 v11, v30, v31
	global_store_dwordx4 v[54:55], v[8:11], off sc1
	s_nop 1
	v_cvt_pk_bf16_f32 v8, v40, v41
	v_cvt_pk_bf16_f32 v9, v48, v49
	v_cvt_pk_bf16_f32 v10, v44, v45
	v_cvt_pk_bf16_f32 v11, v12, v13
	global_store_dwordx4 v[54:55], v[8:11], off offset:16 sc1
	s_andn2_b64 exec, exec, s[22:23]
	s_cbranch_execz .LBB0_237

.LBB0_240:
	v_lshrrev_b32_e32 v5, 9, v4
	v_and_b32_e32 v5, 62, v5
	v_add_u32_e32 v5, 2, v5
	v_cmp_ge_u32_e32 vcc, v221, v5
	s_and_saveexec_b64 s[6:7], vcc
	s_cbranch_execz .LBB0_239
	v_ashrrev_i32_e32 v5, 6, v4
	v_mad_i64_i32 v[8:9], s[20:21], v5, s3, v[6:7]
	global_store_dwordx4 v[8:9], v[0:3], off sc1
	s_branch .LBB0_239
